# instruction selection: GEMM accumulator zeroing between units uses v_mov_b64 (64 instructions) instead of 128 v_mov_b32
# baseline (speedup 1.0000x reference)
; template <class Epi, class Sched, bool ALIGN_EPI = false, bool SP2 = false>
; __device__ __forceinline__ void gemm_phase(PG8_LAS unsigned char* lds, const Gemm g, const Sched& S, const Epi& E) {
;     ...
;     for (;;) {
;         const bool has_next = S.next(ui + 1, nxt);
;         const char* nA = has_next ? (const char*)g.A + (size_t)nxt.pm * tstep : cA; const char* nB = has_next ? (const char*)g.Bt + (size_t)nxt.pn * tstep : cB;
;         for (int t = 0; t < nt; t += 2) {
;     ...
; #pragma unroll
;         for (int a = 0; a < 2; ++a)
; #pragma unroll
;             for (int b = 0; b < 2; ++b)
; #pragma unroll
;                 for (int m = 0; m < 4; ++m)
; #pragma unroll
;                     for (int n = 0; n < 2; ++n) acc[a][b][m][n] = (f32x4){0.f, 0.f, 0.f, 0.f};
.LBB0_131:
	s_ashr_i32 s49, s48, 31
	s_lshl_b64 s[10:11], s[48:49], 19
	s_add_u32 s50, s60, s10
	s_addc_u32 s51, s61, s11
	s_and_b64 s[10:11], s[38:39], exec
	s_cselect_b32 s49, s51, s55
	s_cselect_b32 s73, s50, s54
	s_ashr_i32 s43, s42, 31
	s_lshl_b64 s[10:11], s[42:43], 19
	s_add_u32 s52, s62, s10
	s_addc_u32 s53, s63, s11
	s_and_b64 s[10:11], s[38:39], exec
	s_cselect_b32 s43, s53, s57
	s_cselect_b32 vcc_lo, s52, s56
	s_add_u32 s54, s54, 0x40080
	s_addc_u32 s55, s55, 0
	s_add_u32 vcc_hi, s56, 0x100
	v_mov_b32_e32 v0, 0
	s_addc_u32 s30, s57, 0
	s_mov_b32 s31, -2
	v_mov_b32_e32 v1, v0
	v_mov_b64_e32 v[2:3], 0
	v_mov_b64_e32 v[4:5], 0
	v_mov_b64_e32 v[6:7], 0
	v_mov_b64_e32 v[16:17], 0
	v_mov_b64_e32 v[18:19], 0
	v_mov_b64_e32 v[20:21], 0
	v_mov_b64_e32 v[22:23], 0
	v_mov_b64_e32 v[32:33], 0
	v_mov_b64_e32 v[34:35], 0
	v_mov_b64_e32 v[36:37], 0
	v_mov_b64_e32 v[38:39], 0
	v_mov_b64_e32 v[48:49], 0
	v_mov_b64_e32 v[50:51], 0
	v_mov_b64_e32 v[52:53], 0
	v_mov_b64_e32 v[54:55], 0
	v_mov_b64_e32 v[8:9], 0
	v_mov_b64_e32 v[10:11], 0
	v_mov_b64_e32 v[12:13], 0
	v_mov_b64_e32 v[14:15], 0
	v_mov_b64_e32 v[24:25], 0
	v_mov_b64_e32 v[26:27], 0
	v_mov_b64_e32 v[28:29], 0
	v_mov_b64_e32 v[30:31], 0
	v_mov_b64_e32 v[40:41], 0
	v_mov_b64_e32 v[42:43], 0
	v_mov_b64_e32 v[44:45], 0
	v_mov_b64_e32 v[46:47], 0
	v_mov_b64_e32 v[56:57], 0
	v_mov_b64_e32 v[58:59], 0
	v_mov_b64_e32 v[60:61], 0
	v_mov_b64_e32 v[62:63], 0
	v_mov_b64_e32 v[64:65], 0
	v_mov_b64_e32 v[66:67], 0
	v_mov_b64_e32 v[68:69], 0
	v_mov_b64_e32 v[70:71], 0
	v_mov_b64_e32 v[80:81], 0
	v_mov_b64_e32 v[82:83], 0
	v_mov_b64_e32 v[84:85], 0
	v_mov_b64_e32 v[86:87], 0
	v_mov_b64_e32 v[96:97], 0
	v_mov_b64_e32 v[98:99], 0
	v_mov_b64_e32 v[100:101], 0
	v_mov_b64_e32 v[102:103], 0
	v_mov_b64_e32 v[112:113], 0
	v_mov_b64_e32 v[114:115], 0
	v_mov_b64_e32 v[116:117], 0
	v_mov_b64_e32 v[118:119], 0
	v_mov_b64_e32 v[72:73], 0
	v_mov_b64_e32 v[74:75], 0
	v_mov_b64_e32 v[76:77], 0
	v_mov_b64_e32 v[78:79], 0
	v_mov_b64_e32 v[88:89], 0
	v_mov_b64_e32 v[90:91], 0
	v_mov_b64_e32 v[92:93], 0
	v_mov_b64_e32 v[94:95], 0
	v_mov_b64_e32 v[104:105], 0
	v_mov_b64_e32 v[106:107], 0
	v_mov_b64_e32 v[108:109], 0
	v_mov_b64_e32 v[110:111], 0
	v_mov_b64_e32 v[120:121], 0
	v_mov_b64_e32 v[122:123], 0
	v_mov_b64_e32 v[124:125], 0
	v_mov_b64_e32 v[126:127], 0

; __device__ __forceinline__ void sub_unit(int dil, int Lsub, int nres, int r0, int t0, const bf16* qp, const bf16* __restrict__ kp, const bf16* __restrict__ vp, bf16* op, float* lse, char* lds, const bf16* c1 = nullptr, const bf16* c2 = nullptr, const float* l1 = nullptr, const float* l2 = nullptr) {
;     ...
;     for (int i = 0; i < 6; ++i) { const int ci = tid + 512 * (6 * bt + i), ks = ci >> 3, cc = ci & 7, seg = ks / segk, tk = t0 - 64 + (ks - seg * segk); const bool ok = (tk >= 0) && (tk < Lsub);
;       vst[i] = bf16x8{};
;       if (ok) vst[i] = __builtin_nontemporal_load(reinterpret_cast<const bf16x8*>(vp + ((long)tk * dil + r0 + seg) * LD + cc * 8)); }
.LBB0_357:
	v_mov_b32_e32 v0, 0
	v_mov_b32_e32 v1, v0
	v_mov_b64_e32 v[2:3], 0

; template <class Epi, class Sched, bool ALIGN_EPI = false, bool SP2 = false>
; __device__ __forceinline__ void gemm_phase(PG8_LAS unsigned char* lds, const Gemm g, const Sched& S, const Epi& E) {
;     ...
;     for (;;) {
;         const bool has_next = S.next(ui + 1, nxt);
;         const char* nA = has_next ? (const char*)g.A + (size_t)nxt.pm * tstep : cA; const char* nB = has_next ? (const char*)g.Bt + (size_t)nxt.pn * tstep : cB;
;         for (int t = 0; t < nt; t += 2) {
;     ...
; #pragma unroll
;         for (int a = 0; a < 2; ++a)
; #pragma unroll
;             for (int b = 0; b < 2; ++b)
; #pragma unroll
;                 for (int m = 0; m < 4; ++m)
; #pragma unroll
;                     for (int n = 0; n < 2; ++n) acc[a][b][m][n] = (f32x4){0.f, 0.f, 0.f, 0.f};
.LBB0_417:
	s_ashr_i32 s53, s52, 31
	s_lshl_b64 s[10:11], s[52:53], 19
	s_add_u32 s54, s24, s10
	s_addc_u32 s55, s38, s11
	s_and_b64 s[10:11], s[40:41], exec
	s_cselect_b32 s53, s55, s59
	s_cselect_b32 vcc_lo, s54, s58
	s_ashr_i32 s51, s50, 31
	s_lshl_b64 s[10:11], s[50:51], 19
	s_add_u32 s56, s0, s10
	s_addc_u32 s57, s1, s11
	s_and_b64 s[10:11], s[40:41], exec
	s_cselect_b32 s51, s57, s61
	s_cselect_b32 vcc_hi, s56, s60
	s_add_u32 s58, s58, 0x40080
	s_addc_u32 s59, s59, 0
	s_add_u32 s30, s60, 0x100
	v_mov_b32_e32 v0, 0
	s_addc_u32 s31, s61, 0
	s_mov_b32 s10, -2
	v_mov_b32_e32 v1, v0
	v_mov_b64_e32 v[2:3], 0
	v_mov_b64_e32 v[4:5], 0
	v_mov_b64_e32 v[6:7], 0
	v_mov_b64_e32 v[16:17], 0
	v_mov_b64_e32 v[18:19], 0
	v_mov_b64_e32 v[20:21], 0
	v_mov_b64_e32 v[22:23], 0
	v_mov_b64_e32 v[32:33], 0
	v_mov_b64_e32 v[34:35], 0
	v_mov_b64_e32 v[36:37], 0
	v_mov_b64_e32 v[38:39], 0
	v_mov_b64_e32 v[48:49], 0
	v_mov_b64_e32 v[50:51], 0
	v_mov_b64_e32 v[52:53], 0
	v_mov_b64_e32 v[54:55], 0
	v_mov_b64_e32 v[8:9], 0
	v_mov_b64_e32 v[10:11], 0
	v_mov_b64_e32 v[12:13], 0
	v_mov_b64_e32 v[14:15], 0
	v_mov_b64_e32 v[24:25], 0
	v_mov_b64_e32 v[26:27], 0
	v_mov_b64_e32 v[28:29], 0
	v_mov_b64_e32 v[30:31], 0
	v_mov_b64_e32 v[40:41], 0
	v_mov_b64_e32 v[42:43], 0
	v_mov_b64_e32 v[44:45], 0
	v_mov_b64_e32 v[46:47], 0
	v_mov_b64_e32 v[56:57], 0
	v_mov_b64_e32 v[58:59], 0
	v_mov_b64_e32 v[60:61], 0
	v_mov_b64_e32 v[62:63], 0
	v_mov_b64_e32 v[64:65], 0
	v_mov_b64_e32 v[66:67], 0
	v_mov_b64_e32 v[68:69], 0
	v_mov_b64_e32 v[70:71], 0
	v_mov_b64_e32 v[80:81], 0
	v_mov_b64_e32 v[82:83], 0
	v_mov_b64_e32 v[84:85], 0
	v_mov_b64_e32 v[86:87], 0
	v_mov_b64_e32 v[96:97], 0
	v_mov_b64_e32 v[98:99], 0
	v_mov_b64_e32 v[100:101], 0
	v_mov_b64_e32 v[102:103], 0
	v_mov_b64_e32 v[112:113], 0
	v_mov_b64_e32 v[114:115], 0
	v_mov_b64_e32 v[116:117], 0
	v_mov_b64_e32 v[118:119], 0
	v_mov_b64_e32 v[72:73], 0
	v_mov_b64_e32 v[74:75], 0
	v_mov_b64_e32 v[76:77], 0
	v_mov_b64_e32 v[78:79], 0
	v_mov_b64_e32 v[88:89], 0
	v_mov_b64_e32 v[90:91], 0
	v_mov_b64_e32 v[92:93], 0
	v_mov_b64_e32 v[94:95], 0
	v_mov_b64_e32 v[104:105], 0
	v_mov_b64_e32 v[106:107], 0
	v_mov_b64_e32 v[108:109], 0
	v_mov_b64_e32 v[110:111], 0
	v_mov_b64_e32 v[120:121], 0
	v_mov_b64_e32 v[122:123], 0
	v_mov_b64_e32 v[124:125], 0
	v_mov_b64_e32 v[126:127], 0

; template <class Epi, class Sched, bool ALIGN_EPI = false, bool SP2 = false>
; __device__ __forceinline__ void gemm_phase(PG8_LAS unsigned char* lds, const Gemm g, const Sched& S, const Epi& E) {
;     ...
;     for (;;) {
;         const bool has_next = S.next(ui + 1, nxt);
;         const char* nA = has_next ? (const char*)g.A + (size_t)nxt.pm * tstep : cA; const char* nB = has_next ? (const char*)g.Bt + (size_t)nxt.pn * tstep : cB;
;         for (int t = 0; t < nt; t += 2) {
;     ...
; #pragma unroll
;         for (int a = 0; a < 2; ++a)
; #pragma unroll
;             for (int b = 0; b < 2; ++b)
; #pragma unroll
;                 for (int m = 0; m < 4; ++m)
; #pragma unroll
;                     for (int n = 0; n < 2; ++n) acc[a][b][m][n] = (f32x4){0.f, 0.f, 0.f, 0.f};
.LBB0_437:
	s_ashr_i32 s51, s50, 31
	s_lshl_b64 s[10:11], s[50:51], 19
	s_add_u32 s52, s24, s10
	s_addc_u32 s53, s38, s11
	s_and_b64 s[10:11], s[40:41], exec
	s_cselect_b32 s51, s53, s57
	s_cselect_b32 s72, s52, s56
	s_ashr_i32 s49, s48, 31
	s_lshl_b64 s[10:11], s[48:49], 19
	s_add_u32 s54, s0, s10
	s_addc_u32 s55, s1, s11
	s_and_b64 s[10:11], s[40:41], exec
	s_cselect_b32 s49, s55, s59
	s_cselect_b32 s73, s54, s58
	s_add_u32 s56, s56, 0x40080
	s_addc_u32 s57, s57, 0
	s_add_u32 s30, s58, 0x100
	v_mov_b32_e32 v0, 0
	s_addc_u32 s31, s59, 0
	s_mov_b32 s10, -2
	v_mov_b32_e32 v1, v0
	v_mov_b64_e32 v[2:3], 0
	v_mov_b64_e32 v[4:5], 0
	v_mov_b64_e32 v[6:7], 0
	v_mov_b64_e32 v[16:17], 0
	v_mov_b64_e32 v[18:19], 0
	v_mov_b64_e32 v[20:21], 0
	v_mov_b64_e32 v[22:23], 0
	v_mov_b64_e32 v[32:33], 0
	v_mov_b64_e32 v[34:35], 0
	v_mov_b64_e32 v[36:37], 0
	v_mov_b64_e32 v[38:39], 0
	v_mov_b64_e32 v[48:49], 0
	v_mov_b64_e32 v[50:51], 0
	v_mov_b64_e32 v[52:53], 0
	v_mov_b64_e32 v[54:55], 0
	v_mov_b64_e32 v[8:9], 0
	v_mov_b64_e32 v[10:11], 0
	v_mov_b64_e32 v[12:13], 0
	v_mov_b64_e32 v[14:15], 0
	v_mov_b64_e32 v[24:25], 0
	v_mov_b64_e32 v[26:27], 0
	v_mov_b64_e32 v[28:29], 0
	v_mov_b64_e32 v[30:31], 0
	v_mov_b64_e32 v[40:41], 0
	v_mov_b64_e32 v[42:43], 0
	v_mov_b64_e32 v[44:45], 0
	v_mov_b64_e32 v[46:47], 0
	v_mov_b64_e32 v[56:57], 0
	v_mov_b64_e32 v[58:59], 0
	v_mov_b64_e32 v[60:61], 0
	v_mov_b64_e32 v[62:63], 0
	v_mov_b64_e32 v[64:65], 0
	v_mov_b64_e32 v[66:67], 0
	v_mov_b64_e32 v[68:69], 0
	v_mov_b64_e32 v[70:71], 0
	v_mov_b64_e32 v[80:81], 0
	v_mov_b64_e32 v[82:83], 0
	v_mov_b64_e32 v[84:85], 0
	v_mov_b64_e32 v[86:87], 0
	v_mov_b64_e32 v[96:97], 0
	v_mov_b64_e32 v[98:99], 0
	v_mov_b64_e32 v[100:101], 0
	v_mov_b64_e32 v[102:103], 0
	v_mov_b64_e32 v[112:113], 0
	v_mov_b64_e32 v[114:115], 0
	v_mov_b64_e32 v[116:117], 0
	v_mov_b64_e32 v[118:119], 0
	v_mov_b64_e32 v[72:73], 0
	v_mov_b64_e32 v[74:75], 0
	v_mov_b64_e32 v[76:77], 0
	v_mov_b64_e32 v[78:79], 0
	v_mov_b64_e32 v[88:89], 0
	v_mov_b64_e32 v[90:91], 0
	v_mov_b64_e32 v[92:93], 0
	v_mov_b64_e32 v[94:95], 0
	v_mov_b64_e32 v[104:105], 0
	v_mov_b64_e32 v[106:107], 0
	v_mov_b64_e32 v[108:109], 0
	v_mov_b64_e32 v[110:111], 0
	v_mov_b64_e32 v[120:121], 0
	v_mov_b64_e32 v[122:123], 0
	v_mov_b64_e32 v[124:125], 0
	v_mov_b64_e32 v[126:127], 0

; template <class Epi, class Sched, bool ALIGN_EPI = false, bool SP2 = false>
; __device__ __forceinline__ void gemm_phase(PG8_LAS unsigned char* lds, const Gemm g, const Sched& S, const Epi& E) {
;     ...
;     for (;;) {
;         const bool has_next = S.next(ui + 1, nxt);
;         const char* nA = has_next ? (const char*)g.A + (size_t)nxt.pm * tstep : cA; const char* nB = has_next ? (const char*)g.Bt + (size_t)nxt.pn * tstep : cB;
;         for (int t = 0; t < nt; t += 2) {
;     ...
; #pragma unroll
;         for (int a = 0; a < 2; ++a)
; #pragma unroll
;             for (int b = 0; b < 2; ++b)
; #pragma unroll
;                 for (int m = 0; m < 4; ++m)
; #pragma unroll
;                     for (int n = 0; n < 2; ++n) acc[a][b][m][n] = (f32x4){0.f, 0.f, 0.f, 0.f};
.LBB0_505:
	s_ashr_i32 s55, s54, 31
	s_lshl_b64 s[10:11], s[54:55], 18
	s_add_u32 s56, s16, s10
	s_addc_u32 s57, s17, s11
	s_and_b64 s[10:11], s[40:41], exec
	s_cselect_b32 s55, s57, s61
	s_cselect_b32 s72, s56, s60
	s_ashr_i32 s53, s52, 31
	s_lshl_b64 s[10:11], s[52:53], 18
	s_add_u32 s58, s0, s10
	s_addc_u32 s59, s1, s11
	s_and_b64 s[10:11], s[40:41], exec
	s_cselect_b32 s53, s59, s63
	s_cselect_b32 s73, s58, s62
	s_add_u32 s60, s60, 0x20080
	s_addc_u32 s61, s61, 0
	s_add_u32 s30, s62, 0x100
	v_mov_b32_e32 v0, 0
	s_addc_u32 s31, s63, 0
	s_mov_b32 s10, -2
	v_mov_b32_e32 v1, v0
	v_mov_b64_e32 v[2:3], 0
	v_mov_b64_e32 v[4:5], 0
	v_mov_b64_e32 v[6:7], 0
	v_mov_b64_e32 v[12:13], 0
	v_mov_b64_e32 v[14:15], 0
	v_mov_b64_e32 v[20:21], 0
	v_mov_b64_e32 v[22:23], 0
	v_mov_b64_e32 v[28:29], 0
	v_mov_b64_e32 v[30:31], 0
	v_mov_b64_e32 v[36:37], 0
	v_mov_b64_e32 v[38:39], 0
	v_mov_b64_e32 v[44:45], 0
	v_mov_b64_e32 v[46:47], 0
	v_mov_b64_e32 v[52:53], 0
	v_mov_b64_e32 v[54:55], 0
	v_mov_b64_e32 v[8:9], 0
	v_mov_b64_e32 v[10:11], 0
	v_mov_b64_e32 v[16:17], 0
	v_mov_b64_e32 v[18:19], 0
	v_mov_b64_e32 v[24:25], 0
	v_mov_b64_e32 v[26:27], 0
	v_mov_b64_e32 v[32:33], 0
	v_mov_b64_e32 v[34:35], 0
	v_mov_b64_e32 v[40:41], 0
	v_mov_b64_e32 v[42:43], 0
	v_mov_b64_e32 v[48:49], 0
	v_mov_b64_e32 v[50:51], 0
	v_mov_b64_e32 v[56:57], 0
	v_mov_b64_e32 v[58:59], 0
	v_mov_b64_e32 v[60:61], 0
	v_mov_b64_e32 v[62:63], 0
	v_mov_b64_e32 v[64:65], 0
	v_mov_b64_e32 v[66:67], 0
	v_mov_b64_e32 v[68:69], 0
	v_mov_b64_e32 v[70:71], 0
	v_mov_b64_e32 v[72:73], 0
	v_mov_b64_e32 v[74:75], 0
	v_mov_b64_e32 v[76:77], 0
	v_mov_b64_e32 v[78:79], 0
	v_mov_b64_e32 v[88:89], 0
	v_mov_b64_e32 v[90:91], 0
	v_mov_b64_e32 v[100:101], 0
	v_mov_b64_e32 v[102:103], 0
	v_mov_b64_e32 v[104:105], 0
	v_mov_b64_e32 v[106:107], 0
	v_mov_b64_e32 v[108:109], 0
	v_mov_b64_e32 v[110:111], 0
	v_mov_b64_e32 v[80:81], 0
	v_mov_b64_e32 v[82:83], 0
	v_mov_b64_e32 v[84:85], 0
	v_mov_b64_e32 v[86:87], 0
	v_mov_b64_e32 v[92:93], 0
	v_mov_b64_e32 v[94:95], 0
	v_mov_b64_e32 v[96:97], 0
	v_mov_b64_e32 v[98:99], 0
	v_mov_b64_e32 v[112:113], 0
	v_mov_b64_e32 v[114:115], 0
	v_mov_b64_e32 v[116:117], 0
	v_mov_b64_e32 v[118:119], 0
	v_mov_b64_e32 v[120:121], 0
	v_mov_b64_e32 v[122:123], 0
	v_mov_b64_e32 v[124:125], 0
	v_mov_b64_e32 v[126:127], 0

; template <class Epi, class Sched, bool ALIGN_EPI = false, bool SP2 = false>
; __device__ __forceinline__ void gemm_phase(PG8_LAS unsigned char* lds, const Gemm g, const Sched& S, const Epi& E) {
;     ...
;     for (;;) {
;         const bool has_next = S.next(ui + 1, nxt);
;         const char* nA = has_next ? (const char*)g.A + (size_t)nxt.pm * tstep : cA; const char* nB = has_next ? (const char*)g.Bt + (size_t)nxt.pn * tstep : cB;
;         for (int t = 0; t < nt; t += 2) {
;     ...
; #pragma unroll
;         for (int a = 0; a < 2; ++a)
; #pragma unroll
;             for (int b = 0; b < 2; ++b)
; #pragma unroll
;                 for (int m = 0; m < 4; ++m)
; #pragma unroll
;                     for (int n = 0; n < 2; ++n) acc[a][b][m][n] = (f32x4){0.f, 0.f, 0.f, 0.f};
.LBB0_573:
	s_ashr_i32 s53, s52, 31
	s_lshl_b64 s[10:11], s[52:53], 18
	s_add_u32 s54, s0, s10
	s_addc_u32 s55, s1, s11
	s_and_b64 s[10:11], s[40:41], exec
	s_cselect_b32 s53, s55, s59
	s_cselect_b32 vcc_lo, s54, s58
	s_ashr_i32 s51, s50, 31
	s_lshl_b64 s[10:11], s[50:51], 18
	s_add_u32 s56, s3, s10
	s_addc_u32 s57, s8, s11
	s_and_b64 s[10:11], s[40:41], exec
	s_cselect_b32 s51, s57, s61
	s_cselect_b32 vcc_hi, s56, s60
	s_add_u32 s58, s58, 0x20080
	s_addc_u32 s59, s59, 0
	s_add_u32 s30, s60, 0x100
	v_mov_b32_e32 v0, 0
	s_addc_u32 s31, s61, 0
	s_mov_b32 s10, -2
	v_mov_b32_e32 v1, v0
	v_mov_b64_e32 v[2:3], 0
	v_mov_b64_e32 v[4:5], 0
	v_mov_b64_e32 v[6:7], 0
	v_mov_b64_e32 v[16:17], 0
	v_mov_b64_e32 v[18:19], 0
	v_mov_b64_e32 v[20:21], 0
	v_mov_b64_e32 v[22:23], 0
	v_mov_b64_e32 v[32:33], 0
	v_mov_b64_e32 v[34:35], 0
	v_mov_b64_e32 v[36:37], 0
	v_mov_b64_e32 v[38:39], 0
	v_mov_b64_e32 v[48:49], 0
	v_mov_b64_e32 v[50:51], 0
	v_mov_b64_e32 v[52:53], 0
	v_mov_b64_e32 v[54:55], 0
	v_mov_b64_e32 v[8:9], 0
	v_mov_b64_e32 v[10:11], 0
	v_mov_b64_e32 v[12:13], 0
	v_mov_b64_e32 v[14:15], 0
	v_mov_b64_e32 v[24:25], 0
	v_mov_b64_e32 v[26:27], 0
	v_mov_b64_e32 v[28:29], 0
	v_mov_b64_e32 v[30:31], 0
	v_mov_b64_e32 v[40:41], 0
	v_mov_b64_e32 v[42:43], 0
	v_mov_b64_e32 v[44:45], 0
	v_mov_b64_e32 v[46:47], 0
	v_mov_b64_e32 v[56:57], 0
	v_mov_b64_e32 v[58:59], 0
	v_mov_b64_e32 v[60:61], 0
	v_mov_b64_e32 v[62:63], 0
	v_mov_b64_e32 v[64:65], 0
	v_mov_b64_e32 v[66:67], 0
	v_mov_b64_e32 v[68:69], 0
	v_mov_b64_e32 v[70:71], 0
	v_mov_b64_e32 v[80:81], 0
	v_mov_b64_e32 v[82:83], 0
	v_mov_b64_e32 v[84:85], 0
	v_mov_b64_e32 v[86:87], 0
	v_mov_b64_e32 v[96:97], 0
	v_mov_b64_e32 v[98:99], 0
	v_mov_b64_e32 v[100:101], 0
	v_mov_b64_e32 v[102:103], 0
	v_mov_b64_e32 v[112:113], 0
	v_mov_b64_e32 v[114:115], 0
	v_mov_b64_e32 v[116:117], 0
	v_mov_b64_e32 v[118:119], 0
	v_mov_b64_e32 v[72:73], 0
	v_mov_b64_e32 v[74:75], 0
	v_mov_b64_e32 v[76:77], 0
	v_mov_b64_e32 v[78:79], 0
	v_mov_b64_e32 v[88:89], 0
	v_mov_b64_e32 v[90:91], 0
	v_mov_b64_e32 v[92:93], 0
	v_mov_b64_e32 v[94:95], 0
	v_mov_b64_e32 v[104:105], 0
	v_mov_b64_e32 v[106:107], 0
	v_mov_b64_e32 v[108:109], 0
	v_mov_b64_e32 v[110:111], 0
	v_mov_b64_e32 v[120:121], 0
	v_mov_b64_e32 v[122:123], 0
	v_mov_b64_e32 v[124:125], 0
	v_mov_b64_e32 v[126:127], 0

; template <class Epi, class Sched, bool ALIGN_EPI = false, bool SP2 = false>
; __device__ __forceinline__ void gemm_phase(PG8_LAS unsigned char* lds, const Gemm g, const Sched& S, const Epi& E) {
;     ...
;     for (;;) {
;         const bool has_next = S.next(ui + 1, nxt);
;         const char* nA = has_next ? (const char*)g.A + (size_t)nxt.pm * tstep : cA; const char* nB = has_next ? (const char*)g.Bt + (size_t)nxt.pn * tstep : cB;
;         for (int t = 0; t < nt; t += 2) {
;     ...
; #pragma unroll
;         for (int a = 0; a < 2; ++a)
; #pragma unroll
;             for (int b = 0; b < 2; ++b)
; #pragma unroll
;                 for (int m = 0; m < 4; ++m)
; #pragma unroll
;                     for (int n = 0; n < 2; ++n) acc[a][b][m][n] = (f32x4){0.f, 0.f, 0.f, 0.f};
.LBB0_641:
	s_ashr_i32 s51, s50, 31
	s_lshl_b64 s[10:11], s[50:51], 19
	s_add_u32 s52, s0, s10
	s_addc_u32 s53, s1, s11
	s_and_b64 s[10:11], s[40:41], exec
	s_cselect_b32 s51, s53, s57
	s_cselect_b32 s72, s52, s56
	s_ashr_i32 s49, s48, 31
	s_lshl_b64 s[10:11], s[48:49], 19
	s_add_u32 s54, s3, s10
	s_addc_u32 s55, s8, s11
	s_and_b64 s[10:11], s[40:41], exec
	s_cselect_b32 s49, s55, s59
	s_cselect_b32 s73, s54, s58
	s_add_u32 s56, s56, 0x40080
	s_addc_u32 s57, s57, 0
	s_add_u32 s30, s58, 0x100
	v_mov_b32_e32 v0, 0
	s_addc_u32 s31, s59, 0
	s_mov_b32 s10, -2
	v_mov_b32_e32 v1, v0
	v_mov_b64_e32 v[2:3], 0
	v_mov_b64_e32 v[4:5], 0
	v_mov_b64_e32 v[6:7], 0
	v_mov_b64_e32 v[8:9], 0
	v_mov_b64_e32 v[10:11], 0
	v_mov_b64_e32 v[12:13], 0
	v_mov_b64_e32 v[14:15], 0
	v_mov_b64_e32 v[24:25], 0
	v_mov_b64_e32 v[26:27], 0
	v_mov_b64_e32 v[28:29], 0
	v_mov_b64_e32 v[30:31], 0
	v_mov_b64_e32 v[40:41], 0
	v_mov_b64_e32 v[42:43], 0
	v_mov_b64_e32 v[44:45], 0
	v_mov_b64_e32 v[46:47], 0
	v_mov_b64_e32 v[16:17], 0
	v_mov_b64_e32 v[18:19], 0
	v_mov_b64_e32 v[20:21], 0
	v_mov_b64_e32 v[22:23], 0
	v_mov_b64_e32 v[32:33], 0
	v_mov_b64_e32 v[34:35], 0
	v_mov_b64_e32 v[36:37], 0
	v_mov_b64_e32 v[38:39], 0
	v_mov_b64_e32 v[48:49], 0
	v_mov_b64_e32 v[50:51], 0
	v_mov_b64_e32 v[52:53], 0
	v_mov_b64_e32 v[54:55], 0
	v_mov_b64_e32 v[56:57], 0
	v_mov_b64_e32 v[58:59], 0
	v_mov_b64_e32 v[60:61], 0
	v_mov_b64_e32 v[62:63], 0
	v_mov_b64_e32 v[64:65], 0
	v_mov_b64_e32 v[66:67], 0
	v_mov_b64_e32 v[68:69], 0
	v_mov_b64_e32 v[70:71], 0
	v_mov_b64_e32 v[72:73], 0
	v_mov_b64_e32 v[74:75], 0
	v_mov_b64_e32 v[76:77], 0
	v_mov_b64_e32 v[78:79], 0
	v_mov_b64_e32 v[88:89], 0
	v_mov_b64_e32 v[90:91], 0
	v_mov_b64_e32 v[92:93], 0
	v_mov_b64_e32 v[94:95], 0
	v_mov_b64_e32 v[104:105], 0
	v_mov_b64_e32 v[106:107], 0
	v_mov_b64_e32 v[108:109], 0
	v_mov_b64_e32 v[110:111], 0
	v_mov_b64_e32 v[80:81], 0
	v_mov_b64_e32 v[82:83], 0
	v_mov_b64_e32 v[84:85], 0
	v_mov_b64_e32 v[86:87], 0
	v_mov_b64_e32 v[96:97], 0
	v_mov_b64_e32 v[98:99], 0
	v_mov_b64_e32 v[100:101], 0
	v_mov_b64_e32 v[102:103], 0
	v_mov_b64_e32 v[112:113], 0
	v_mov_b64_e32 v[114:115], 0
	v_mov_b64_e32 v[116:117], 0
	v_mov_b64_e32 v[118:119], 0
	v_mov_b64_e32 v[120:121], 0
	v_mov_b64_e32 v[122:123], 0
	v_mov_b64_e32 v[124:125], 0
	v_mov_b64_e32 v[126:127], 0

; template <class Epi, class Sched, bool ALIGN_EPI = false, bool SP2 = false>
; __device__ __forceinline__ void gemm_phase(PG8_LAS unsigned char* lds, const Gemm g, const Sched& S, const Epi& E) {
;     ...
;     for (;;) {
;         const bool has_next = S.next(ui + 1, nxt);
;         const char* nA = has_next ? (const char*)g.A + (size_t)nxt.pm * tstep : cA; const char* nB = has_next ? (const char*)g.Bt + (size_t)nxt.pn * tstep : cB;
;         for (int t = 0; t < nt; t += 2) {
;     ...
; #pragma unroll
;         for (int a = 0; a < 2; ++a)
; #pragma unroll
;             for (int b = 0; b < 2; ++b)
; #pragma unroll
;                 for (int m = 0; m < 4; ++m)
; #pragma unroll
;                     for (int n = 0; n < 2; ++n) acc[a][b][m][n] = (f32x4){0.f, 0.f, 0.f, 0.f};
.LBB0_766:
	s_ashr_i32 s55, s54, 31
	s_lshl_b64 s[10:11], s[54:55], 19
	s_add_u32 s56, s0, s10
	s_addc_u32 s57, s1, s11
	s_and_b64 s[10:11], s[42:43], exec
	s_cselect_b32 s53, s57, s61
	s_cselect_b32 s55, s56, s60
	s_ashr_i32 s51, s50, 31
	s_lshl_b64 s[10:11], s[50:51], 19
	s_add_u32 s58, s3, s10
	s_addc_u32 s59, s8, s11
	s_and_b64 s[10:11], s[42:43], exec
	s_cselect_b32 s51, s59, s63
	s_cselect_b32 s72, s58, s62
	s_add_u32 s60, s60, 0x40080
	s_addc_u32 s61, s61, 0
	s_add_u32 s30, s62, 0x100
	v_mov_b32_e32 v0, 0
	s_addc_u32 s31, s63, 0
	s_mov_b32 s10, -2
	v_mov_b32_e32 v1, v0
	v_mov_b64_e32 v[2:3], 0
	v_mov_b64_e32 v[4:5], 0
	v_mov_b64_e32 v[6:7], 0
	v_mov_b64_e32 v[16:17], 0
	v_mov_b64_e32 v[18:19], 0
	v_mov_b64_e32 v[20:21], 0
	v_mov_b64_e32 v[22:23], 0
	v_mov_b64_e32 v[32:33], 0
	v_mov_b64_e32 v[34:35], 0
	v_mov_b64_e32 v[36:37], 0
	v_mov_b64_e32 v[38:39], 0
	v_mov_b64_e32 v[48:49], 0
	v_mov_b64_e32 v[50:51], 0
	v_mov_b64_e32 v[52:53], 0
	v_mov_b64_e32 v[54:55], 0
	v_mov_b64_e32 v[8:9], 0
	v_mov_b64_e32 v[10:11], 0
	v_mov_b64_e32 v[12:13], 0
	v_mov_b64_e32 v[14:15], 0
	v_mov_b64_e32 v[24:25], 0
	v_mov_b64_e32 v[26:27], 0
	v_mov_b64_e32 v[28:29], 0
	v_mov_b64_e32 v[30:31], 0
	v_mov_b64_e32 v[40:41], 0
	v_mov_b64_e32 v[42:43], 0
	v_mov_b64_e32 v[44:45], 0
	v_mov_b64_e32 v[46:47], 0
	v_mov_b64_e32 v[56:57], 0
	v_mov_b64_e32 v[58:59], 0
	v_mov_b64_e32 v[60:61], 0
	v_mov_b64_e32 v[62:63], 0
	v_mov_b64_e32 v[64:65], 0
	v_mov_b64_e32 v[66:67], 0
	v_mov_b64_e32 v[68:69], 0
	v_mov_b64_e32 v[70:71], 0
	v_mov_b64_e32 v[80:81], 0
	v_mov_b64_e32 v[82:83], 0
	v_mov_b64_e32 v[84:85], 0
	v_mov_b64_e32 v[86:87], 0
	v_mov_b64_e32 v[96:97], 0
	v_mov_b64_e32 v[98:99], 0
	v_mov_b64_e32 v[100:101], 0
	v_mov_b64_e32 v[102:103], 0
	v_mov_b64_e32 v[112:113], 0
	v_mov_b64_e32 v[114:115], 0
	v_mov_b64_e32 v[116:117], 0
	v_mov_b64_e32 v[118:119], 0
	v_mov_b64_e32 v[72:73], 0
	v_mov_b64_e32 v[74:75], 0
	v_mov_b64_e32 v[76:77], 0
	v_mov_b64_e32 v[78:79], 0
	v_mov_b64_e32 v[88:89], 0
	v_mov_b64_e32 v[90:91], 0
	v_mov_b64_e32 v[92:93], 0
	v_mov_b64_e32 v[94:95], 0
	v_mov_b64_e32 v[104:105], 0
	v_mov_b64_e32 v[106:107], 0
	v_mov_b64_e32 v[108:109], 0
	v_mov_b64_e32 v[110:111], 0
	v_mov_b64_e32 v[120:121], 0
	v_mov_b64_e32 v[122:123], 0
	v_mov_b64_e32 v[124:125], 0
	v_mov_b64_e32 v[126:127], 0

; template <class Epi, class Sched, bool ALIGN_EPI = false, bool SP2 = false>
; __device__ __forceinline__ void gemm_phase(PG8_LAS unsigned char* lds, const Gemm g, const Sched& S, const Epi& E) {
;     ...
; #pragma unroll
;         for (int a = 0; a < 2; ++a)
; #pragma unroll
;             for (int b = 0; b < 2; ++b)
; #pragma unroll
;                 for (int m = 0; m < 4; ++m)
; #pragma unroll
;                     for (int n = 0; n < 2; ++n) acc[a][b][m][n] = (f32x4){0.f, 0.f, 0.f, 0.f};
.LBB0_838:
	s_add_u32 s30, s58, 0x100
	v_mov_b32_e32 v0, 0
	s_addc_u32 s31, s59, 0
	s_mov_b32 s10, -2
	v_mov_b32_e32 v1, v0
	v_mov_b64_e32 v[2:3], 0
	v_mov_b64_e32 v[4:5], 0
	v_mov_b64_e32 v[6:7], 0
	v_mov_b64_e32 v[8:9], 0
	v_mov_b64_e32 v[10:11], 0
	v_mov_b64_e32 v[12:13], 0
	v_mov_b64_e32 v[14:15], 0
	v_mov_b64_e32 v[24:25], 0
	v_mov_b64_e32 v[26:27], 0
	v_mov_b64_e32 v[28:29], 0
	v_mov_b64_e32 v[30:31], 0
	v_mov_b64_e32 v[40:41], 0
	v_mov_b64_e32 v[42:43], 0
	v_mov_b64_e32 v[44:45], 0
	v_mov_b64_e32 v[46:47], 0
	v_mov_b64_e32 v[16:17], 0
	v_mov_b64_e32 v[18:19], 0
	v_mov_b64_e32 v[20:21], 0
	v_mov_b64_e32 v[22:23], 0
	v_mov_b64_e32 v[32:33], 0
	v_mov_b64_e32 v[34:35], 0
	v_mov_b64_e32 v[36:37], 0
	v_mov_b64_e32 v[38:39], 0
	v_mov_b64_e32 v[48:49], 0
	v_mov_b64_e32 v[50:51], 0
	v_mov_b64_e32 v[52:53], 0
	v_mov_b64_e32 v[54:55], 0
	v_mov_b64_e32 v[56:57], 0
	v_mov_b64_e32 v[58:59], 0
	v_mov_b64_e32 v[60:61], 0
	v_mov_b64_e32 v[62:63], 0
	v_mov_b64_e32 v[64:65], 0
	v_mov_b64_e32 v[66:67], 0
	v_mov_b64_e32 v[68:69], 0
	v_mov_b64_e32 v[70:71], 0
	v_mov_b64_e32 v[72:73], 0
	v_mov_b64_e32 v[74:75], 0
	v_mov_b64_e32 v[76:77], 0
	v_mov_b64_e32 v[78:79], 0
	v_mov_b64_e32 v[88:89], 0
	v_mov_b64_e32 v[90:91], 0
	v_mov_b64_e32 v[92:93], 0
	v_mov_b64_e32 v[94:95], 0
	v_mov_b64_e32 v[104:105], 0
	v_mov_b64_e32 v[106:107], 0
	v_mov_b64_e32 v[108:109], 0
	v_mov_b64_e32 v[110:111], 0
	v_mov_b64_e32 v[80:81], 0
	v_mov_b64_e32 v[82:83], 0
	v_mov_b64_e32 v[84:85], 0
	v_mov_b64_e32 v[86:87], 0
	v_mov_b64_e32 v[96:97], 0
	v_mov_b64_e32 v[98:99], 0
	v_mov_b64_e32 v[100:101], 0
	v_mov_b64_e32 v[102:103], 0
	v_mov_b64_e32 v[112:113], 0
	v_mov_b64_e32 v[114:115], 0
	v_mov_b64_e32 v[116:117], 0
	v_mov_b64_e32 v[118:119], 0
	v_mov_b64_e32 v[120:121], 0
	v_mov_b64_e32 v[122:123], 0
	v_mov_b64_e32 v[124:125], 0
	v_mov_b64_e32 v[126:127], 0
